# mem-kv tail GEMM: software L2 prefetch of remaining k-tiles
# baseline (speedup 1.0000x reference)
; DI int tid_op() { int t = threadIdx.x & 255; asm volatile("" : "+v"(t)); return t; }
; #define VB ((int)blockIdx.x * 2 + vhalf())
; DI void gemm_accum(f32x16 (&acc)[2][2], const bf16_t* A, int lda, const bf16_t* Bt, int ldb, int nk, unsigned char* smem) {
;     const int tid = tid_op(), lane = tid & 63, w = tid >> 6, wr = w >> 1, wc = w & 1, r = lane & 31, h = lane >> 5;
;     bf16_t* sA = (bf16_t*)smem;
;     bf16_t* sB = sA + 2 * TILE_E;
;     u32x4 ra[4], rb[4];
;     const unsigned oa = (unsigned)(((tid >> 3) * lda + (tid & 7) * 8) * 2), ob = (unsigned)(((tid >> 3) * ldb + (tid & 7) * 8) * 2);
;     const unsigned sa = (unsigned)(lda * 64), sb = (unsigned)(ldb * 64);
;     g_load(ra, rb, A, oa, sa, Bt, ob, sb);
;     __syncthreads();
;     g_store(ra, rb, sA, sB, tid);
; #pragma unroll 1
;     for (int kt = 0; kt < nk; ++kt) {
;         const int buf = kt & 1;
;         if (kt + 1 < nk) g_load(ra, rb, A + (kt + 1) * 64, oa, sa, Bt + (kt + 1) * 64, ob, sb);
; DI void phase1(const Params& p, int l, unsigned char* smem) {
;     ...
;         for (int t = VB - 256; t >= 0 && t < 32; t += VG) {
;             const int m0 = (t >> 2) * 128, n0 = (t & 3) * 128;
;             f32x16 acc[2][2]; zero4(acc);
;             gemm_accum(acc, (const bf16_t*)(ws + O_MEMB) + (size_t)m0 * 1024, 1024, (const bf16_t*)(ws + O_WMEM + l * SZ_WMEM) + (size_t)n0 * 1024, 1024, 16, hs);
.LBB0_515:
	s_lshl_b32 s8, s19, 11
	s_and_b32 s25, s8, 0xc0000
	s_lshl_b32 s8, s22, 11
	s_and_b32 s26, s8, 0x1c0000
	s_lshl_b32 s8, s12, 5
	s_and_b32 s24, s8, 0x380
	s_lshl_b32 s8, s12, 7
	s_and_b32 s23, s8, 0x180
	s_lshl_b32 s8, s24, 11
	v_mov_b32_e32 v12, v215
	s_add_u32 s8, s13, s8
	s_addc_u32 s9, s14, 0
	v_lshlrev_b32_e32 v0, 4, v12
	s_lshl_b32 s10, s23, 11
	v_ashrrev_i32_e32 v13, 3, v12
	v_and_b32_e32 v14, 0x70, v0
	s_add_u32 s10, s15, s10
	v_lshl_or_b32 v0, v13, 11, v14
	s_addc_u32 s11, s16, 0
	v_lshl_add_u64 v[2:3], s[8:9], 0, v[0:1]
	v_lshl_add_u64 v[4:5], s[10:11], 0, v[0:1]
	global_load_dwordx4 v[66:69], v[2:3], off
	global_load_dwordx4 v[70:73], v[4:5], off
	v_add_u32_e32 v2, 0x10000, v0
	v_mov_b32_e32 v3, v1
	v_lshl_add_u64 v[4:5], s[8:9], 0, v[2:3]
	v_lshl_add_u64 v[6:7], s[10:11], 0, v[2:3]
	global_load_dwordx4 v[74:77], v[4:5], off
	global_load_dwordx4 v[78:81], v[6:7], off
	v_add_u32_e32 v4, 0x20000, v0
	v_mov_b32_e32 v5, v1
	v_lshl_add_u64 v[6:7], s[8:9], 0, v[4:5]
	v_lshl_add_u64 v[8:9], s[10:11], 0, v[4:5]
	global_load_dwordx4 v[82:85], v[6:7], off
	global_load_dwordx4 v[86:89], v[8:9], off
	v_add_u32_e32 v6, 0x30000, v0
	v_mov_b32_e32 v7, v1
	v_lshl_add_u64 v[8:9], s[8:9], 0, v[6:7]
	v_lshl_add_u64 v[10:11], s[10:11], 0, v[6:7]
	global_load_dwordx4 v[90:93], v[8:9], off
	global_load_dwordx4 v[94:97], v[10:11], off
	v_and_b32_e32 v204, 0x7f, v215
	v_lshlrev_b32_e32 v204, 11, v204
	v_cmp_gt_u32_e32 vcc, 0x80, v215
	v_mov_b32_e32 v205, s8
	v_mov_b32_e32 v206, s10
	v_cndmask_b32_e32 v206, v206, v205, vcc
	v_mov_b32_e32 v205, s9
	v_mov_b32_e32 v207, s11
	v_cndmask_b32_e32 v207, v207, v205, vcc
	v_add_co_u32_e32 v206, vcc, v206, v204
	s_nop 1
	v_addc_co_u32_e32 v207, vcc, 0, v207, vcc
	global_load_dword v250, v[206:207], off offset:384
	global_load_dword v250, v[206:207], off offset:512
	global_load_dword v250, v[206:207], off offset:640
	global_load_dword v250, v[206:207], off offset:768
	global_load_dword v250, v[206:207], off offset:896
	global_load_dword v250, v[206:207], off offset:1024
	global_load_dword v250, v[206:207], off offset:1152
	global_load_dword v250, v[206:207], off offset:1280
	global_load_dword v250, v[206:207], off offset:1408
	global_load_dword v250, v[206:207], off offset:1536
	global_load_dword v250, v[206:207], off offset:1664
	global_load_dword v250, v[206:207], off offset:1792
	global_load_dword v250, v[206:207], off offset:1920
	s_add_u32 s8, s17, s25
	v_add_u32_e32 v9, 0x100, v12
	v_add_u32_e32 v10, 0x200, v12
	v_add_u32_e32 v11, 0x300, v12
	s_addc_u32 s9, s18, 0
	v_and_b32_e32 v8, 31, v12
	v_lshrrev_b32_e32 v15, 1, v12
	v_and_b32_e32 v12, 0x5f, v12
	s_movk_i32 s1, 0x48
	v_lshrrev_b32_e32 v9, 3, v9
	v_lshrrev_b32_e32 v10, 3, v10
	v_lshrrev_b32_e32 v11, 3, v11
	v_lshl_add_u64 v[106:107], s[8:9], 0, v[6:7]
	v_lshl_add_u64 v[108:109], s[8:9], 0, v[4:5]
	v_lshl_add_u64 v[110:111], s[8:9], 0, v[2:3]
	v_lshl_add_u64 v[112:113], s[8:9], 0, v[0:1]
	s_add_u32 s8, s20, s26
	v_mul_lo_u32 v99, v13, s1
	v_and_or_b32 v8, v15, s93, v8
	v_and_b32_e32 v13, 16, v15
	v_mul_u32_u24_e32 v12, 0x90, v12
	v_add_u32_e32 v101, s3, v14
	v_mul_lo_u32 v103, v9, s1
	v_mul_lo_u32 v105, v10, s1
	v_mul_lo_u32 v124, v11, s1
	s_addc_u32 s9, s21, 0
	v_mul_lo_u32 v8, v8, s92
	v_add3_u32 v125, s3, v12, v13
	v_lshl_add_u32 v9, v99, 1, v101
	v_lshl_add_u32 v10, v103, 1, v101
	v_lshl_add_u32 v11, v105, 1, v101
	v_lshl_add_u32 v12, v124, 1, v101
	v_lshl_add_u64 v[118:119], s[8:9], 0, v[2:3]
	v_mov_b32_e32 v2, 0
	v_add3_u32 v126, s3, v8, v13
	s_waitcnt vmcnt(0) lgkmcnt(0)
	s_barrier
	v_lshl_add_u64 v[114:115], s[8:9], 0, v[6:7]
	v_lshl_add_u64 v[116:117], s[8:9], 0, v[4:5]
	v_lshl_add_u64 v[120:121], s[8:9], 0, v[0:1]
	global_load_dwordx4 v[140:143], v[120:121], off offset:0
	global_load_dwordx4 v[144:147], v[112:113], off offset:0
	global_load_dwordx4 v[148:151], v[118:119], off offset:0
	global_load_dwordx4 v[152:155], v[110:111], off offset:0
	global_load_dwordx4 v[156:159], v[116:117], off offset:0
	global_load_dwordx4 v[160:163], v[108:109], off offset:0
	global_load_dwordx4 v[164:167], v[114:115], off offset:0
	global_load_dwordx4 v[168:171], v[106:107], off offset:0
	global_load_dwordx4 v[172:175], v[120:121], off offset:128
	global_load_dwordx4 v[176:179], v[112:113], off offset:128
	global_load_dwordx4 v[180:183], v[118:119], off offset:128
	global_load_dwordx4 v[184:187], v[110:111], off offset:128
	global_load_dwordx4 v[188:191], v[116:117], off offset:128
	global_load_dwordx4 v[192:195], v[108:109], off offset:128
	global_load_dwordx4 v[196:199], v[114:115], off offset:128
	global_load_dwordx4 v[200:203], v[106:107], off offset:128
	s_mov_b32 s25, 0
	s_mov_b64 s[8:9], 0
	v_mov_b32_e32 v3, v2
	v_mov_b32_e32 v4, v2
	v_mov_b32_e32 v5, v2
	v_mov_b32_e32 v6, v2
	v_mov_b32_e32 v7, v2
	v_mov_b32_e32 v8, v2
	v_mov_b32_e32 v13, v2
	v_mov_b32_e32 v14, v2
	v_mov_b32_e32 v15, v2
	v_mov_b32_e32 v16, v2
	v_mov_b32_e32 v17, v2
	v_mov_b32_e32 v18, v2
	v_mov_b32_e32 v19, v2
	v_mov_b32_e32 v20, v2
	ds_write_b128 v9, v[66:69]
	ds_write_b128 v9, v[70:73] offset:36864
	ds_write_b128 v10, v[74:77]
	ds_write_b128 v10, v[78:81] offset:36864
	ds_write_b128 v11, v[82:85]
	ds_write_b128 v11, v[86:89] offset:36864
	ds_write_b128 v12, v[90:93]
	ds_write_b128 v12, v[94:97] offset:36864
	v_mov_b32_e32 v9, v2
	v_mov_b32_e32 v10, v2
	v_mov_b32_e32 v11, v2
	v_mov_b32_e32 v12, v2
	v_mov_b32_e32 v21, v2
	v_mov_b32_e32 v22, v2
	v_mov_b32_e32 v23, v2
	v_mov_b32_e32 v24, v2
	v_mov_b32_e32 v25, v2
	v_mov_b32_e32 v26, v2
	v_mov_b32_e32 v27, v2
	v_mov_b32_e32 v28, v2
	v_mov_b32_e32 v29, v2
	v_mov_b32_e32 v30, v2
	v_mov_b32_e32 v31, v2
	v_mov_b32_e32 v32, v2
	v_mov_b32_e32 v33, v2
	v_mov_b32_e32 v34, v2
	v_mov_b32_e32 v35, v2
	v_mov_b32_e32 v36, v2
	v_mov_b32_e32 v37, v2
	v_mov_b32_e32 v38, v2
	v_mov_b32_e32 v39, v2
	v_mov_b32_e32 v40, v2
	v_mov_b32_e32 v41, v2
	v_mov_b32_e32 v42, v2
	v_mov_b32_e32 v43, v2
	v_mov_b32_e32 v44, v2
	v_mov_b32_e32 v45, v2
	v_mov_b32_e32 v46, v2
	v_mov_b32_e32 v47, v2
	v_mov_b32_e32 v48, v2
	v_mov_b32_e32 v49, v2
	v_mov_b32_e32 v50, v2
	v_mov_b32_e32 v51, v2
	v_mov_b32_e32 v52, v2
	v_mov_b32_e32 v53, v2
	v_mov_b32_e32 v54, v2
	v_mov_b32_e32 v55, v2
	v_mov_b32_e32 v56, v2
	v_mov_b32_e32 v57, v2
	v_mov_b32_e32 v58, v2
	v_mov_b32_e32 v59, v2
	v_mov_b32_e32 v60, v2
	v_mov_b32_e32 v61, v2
	v_mov_b32_e32 v62, v2
	v_mov_b32_e32 v63, v2
	v_mov_b32_e32 v64, v2
	v_mov_b32_e32 v65, v2
	v_lshl_add_u32 v208, v99, 1, v101
	v_lshl_add_u32 v209, v103, 1, v101
	v_lshl_add_u32 v210, v105, 1, v101
	v_lshl_add_u32 v211, v124, 1, v101
	s_branch .LBB0_517
